# k40 + grid barrier w_out -> FF1 as row-panel rendezvous (4 arrivals per panel; the 16 sample row-step WGs wait for the whole grid)
# baseline (speedup 1.0000x reference)
.LBB0_775:
	s_waitcnt vmcnt(0)
	s_and_b64 vcc, exec, s[94:95]
	s_barrier
	s_cbranch_vccnz .LBB0_829
	v_mbcnt_lo_u32_b32 v0, -1, 0
	v_mbcnt_hi_u32_b32 v0, -1, v0
	s_nop 0
	v_cmp_eq_u32_e32 vcc, 0, v0
	s_and_saveexec_b64 s[8:9], vcc
	s_cbranch_execz .LBB0_828
	buffer_wbl2 sc1
	s_and_b32 s10, s2, 7
	s_lshl_b32 s10, s10, 3
	s_bfe_u32 s11, s2, 0x30003
	s_or_b32 s10, s10, s11
	s_lshl_b32 s10, s10, 8
	s_add_u32 s12, s0, 0x14000
	s_addc_u32 s13, s1, 0
	s_add_u32 s12, s12, s10
	s_addc_u32 s13, s13, 0
	s_add_u32 s14, s0, 0x28500
	s_addc_u32 s15, s1, 0
	v_mov_b32_e32 v0, 0
	v_mov_b32_e32 v1, 1
	s_waitcnt vmcnt(0) lgkmcnt(0)
	global_atomic_add v0, v1, s[12:13]
	global_atomic_add v0, v1, s[14:15]
	s_mov_b32 s16, 0
.Lp6_wait_panel:
	global_load_dword v2, v0, s[12:13] sc1
	s_waitcnt vmcnt(0)
	v_readfirstlane_b32 s17, v2
	s_cmp_ge_u32 s17, 4
	s_cbranch_scc1 .Lp6_panel_ok
	s_sleep 1
	s_add_i32 s16, s16, 1
	s_cmp_lt_u32 s16, 0x40001
	s_cbranch_scc1 .Lp6_wait_panel
.Lp6_panel_ok:
	s_cmp_lt_u32 s2, 16
	s_cbranch_scc0 .Lp6_acq
	s_mov_b32 s16, 0
.Lp6_wait_all:
	global_load_dword v2, v0, s[14:15] sc1
	s_waitcnt vmcnt(0)
	v_readfirstlane_b32 s17, v2
	s_cmp_ge_u32 s17, s33
	s_cbranch_scc1 .Lp6_acq
	s_sleep 1
	s_add_i32 s16, s16, 1
	s_cmp_lt_u32 s16, 0x40001
	s_cbranch_scc1 .Lp6_wait_all
.Lp6_acq:
	buffer_inv sc1
	s_waitcnt vmcnt(0)
.LBB0_828:
	s_or_b64 exec, exec, s[8:9]
